# last-layer FFN pre-norm fused into the mixer output-projection epilogue (row sums exchanged per row tile, H written directly); pre-norm phase and its grid barrier skipped in the last layer
# speedup vs baseline: 1.0211x; 1.0004x over previous
.Lf7_start:
	v_readlane_b32 s88, v254, 50
	v_readlane_b32 s89, v254, 51
	s_mov_b32 s17, s20
	v_mov_b32_e32 v153, v150
	s_lshl_b32 s28, s16, 8
	s_add_i32 s28, s28, s94
	v_add_u32_e32 v152, s28, v152
	s_mul_i32 s28, s22, 0xc000
	s_add_u32 s24, s73, s28
	s_addc_u32 s25, s92, 0
	global_load_dwordx4 v[128:131], v153, s[24:25] offset:0
	global_load_dwordx4 v[132:135], v153, s[24:25] offset:64
	global_load_dwordx4 v[136:139], v153, s[24:25] offset:512
	global_load_dwordx4 v[140:143], v153, s[24:25] offset:576
	v_readlane_b32 s100, v253, 50
	v_readlane_b32 s101, v253, 51
	s_add_u32 s100, s100, 0
	s_addc_u32 s101, s101, 0
	v_add_u32_e32 v154, 0, v152
	v_lshl_add_u32 v154, v154, 13, v153
	global_load_dwordx4 v[178:181], v154, s[100:101] offset:0
	global_load_dwordx4 v[182:185], v154, s[100:101] offset:64
	global_load_dwordx4 v[186:189], v154, s[100:101] offset:512
	global_load_dwordx4 v[190:193], v154, s[100:101] offset:576
	v_add_u32_e32 v154, 16, v152
	v_lshl_add_u32 v154, v154, 13, v153
	global_load_dwordx4 v[194:197], v154, s[100:101] offset:0
	global_load_dwordx4 v[198:201], v154, s[100:101] offset:64
	global_load_dwordx4 v[202:205], v154, s[100:101] offset:512
	global_load_dwordx4 v[206:209], v154, s[100:101] offset:576
	v_add_u32_e32 v154, 32, v152
	v_lshl_add_u32 v154, v154, 13, v153
	global_load_dwordx4 v[210:213], v154, s[100:101] offset:0
	global_load_dwordx4 v[232:235], v154, s[100:101] offset:64
	global_load_dwordx4 v[236:239], v154, s[100:101] offset:512
	global_load_dwordx4 v[240:243], v154, s[100:101] offset:576
	v_add_u32_e32 v154, 48, v152
	v_lshl_add_u32 v154, v154, 13, v153
	global_load_dwordx4 v[244:247], v154, s[100:101] offset:0
	global_load_dwordx4 v[248:251], v154, s[100:101] offset:64
	global_load_dwordx4 v[162:165], v154, s[100:101] offset:512
	global_load_dwordx4 v[166:169], v154, s[100:101] offset:576
	s_waitcnt vmcnt(0)
	v_pk_fma_f32 v[124:125], v[124:125], v[128:129], v[178:179]
	v_pk_fma_f32 v[126:127], v[126:127], v[130:131], v[180:181]
	v_pk_fma_f32 v[120:121], v[120:121], v[132:133], v[182:183]
	v_pk_fma_f32 v[122:123], v[122:123], v[134:135], v[184:185]
	v_pk_fma_f32 v[116:117], v[116:117], v[136:137], v[186:187]
	v_pk_fma_f32 v[118:119], v[118:119], v[138:139], v[188:189]
	v_pk_fma_f32 v[104:105], v[104:105], v[140:141], v[190:191]
	v_pk_fma_f32 v[106:107], v[106:107], v[142:143], v[192:193]
	v_pk_fma_f32 v[112:113], v[112:113], v[128:129], v[194:195]
	v_pk_fma_f32 v[114:115], v[114:115], v[130:131], v[196:197]
	v_pk_fma_f32 v[108:109], v[108:109], v[132:133], v[198:199]
	v_pk_fma_f32 v[110:111], v[110:111], v[134:135], v[200:201]
	v_pk_fma_f32 v[96:97], v[96:97], v[136:137], v[202:203]
	v_pk_fma_f32 v[98:99], v[98:99], v[138:139], v[204:205]
	v_pk_fma_f32 v[88:89], v[88:89], v[140:141], v[206:207]
	v_pk_fma_f32 v[90:91], v[90:91], v[142:143], v[208:209]
	v_pk_fma_f32 v[100:101], v[100:101], v[128:129], v[210:211]
	v_pk_fma_f32 v[102:103], v[102:103], v[130:131], v[212:213]
	v_pk_fma_f32 v[92:93], v[92:93], v[132:133], v[232:233]
	v_pk_fma_f32 v[94:95], v[94:95], v[134:135], v[234:235]
	v_pk_fma_f32 v[80:81], v[80:81], v[136:137], v[236:237]
	v_pk_fma_f32 v[82:83], v[82:83], v[138:139], v[238:239]
	v_pk_fma_f32 v[72:73], v[72:73], v[140:141], v[240:241]
	v_pk_fma_f32 v[74:75], v[74:75], v[142:143], v[242:243]
	v_pk_fma_f32 v[84:85], v[84:85], v[128:129], v[244:245]
	v_pk_fma_f32 v[86:87], v[86:87], v[130:131], v[246:247]
	v_pk_fma_f32 v[76:77], v[76:77], v[132:133], v[248:249]
	v_pk_fma_f32 v[78:79], v[78:79], v[134:135], v[250:251]
	v_pk_fma_f32 v[68:69], v[68:69], v[136:137], v[162:163]
	v_pk_fma_f32 v[70:71], v[70:71], v[138:139], v[164:165]
	v_pk_fma_f32 v[64:65], v[64:65], v[140:141], v[166:167]
	v_pk_fma_f32 v[66:67], v[66:67], v[142:143], v[168:169]
	v_add_u32_e32 v154, 0, v152
	v_lshl_add_u32 v154, v154, 13, v153
	global_store_dwordx4 v154, v[124:127], s[100:101] offset:0 sc1
	global_store_dwordx4 v154, v[120:123], s[100:101] offset:64 sc1
	global_store_dwordx4 v154, v[116:119], s[100:101] offset:512 sc1
	global_store_dwordx4 v154, v[104:107], s[100:101] offset:576 sc1
	v_add_u32_e32 v154, 16, v152
	v_lshl_add_u32 v154, v154, 13, v153
	global_store_dwordx4 v154, v[112:115], s[100:101] offset:0 sc1
	global_store_dwordx4 v154, v[108:111], s[100:101] offset:64 sc1
	global_store_dwordx4 v154, v[96:99], s[100:101] offset:512 sc1
	global_store_dwordx4 v154, v[88:91], s[100:101] offset:576 sc1
	v_add_u32_e32 v154, 32, v152
	v_lshl_add_u32 v154, v154, 13, v153
	global_store_dwordx4 v154, v[100:103], s[100:101] offset:0 sc1
	global_store_dwordx4 v154, v[92:95], s[100:101] offset:64 sc1
	global_store_dwordx4 v154, v[80:83], s[100:101] offset:512 sc1
	global_store_dwordx4 v154, v[72:75], s[100:101] offset:576 sc1
	v_add_u32_e32 v154, 48, v152
	v_lshl_add_u32 v154, v154, 13, v153
	global_store_dwordx4 v154, v[84:87], s[100:101] offset:0 sc1
	global_store_dwordx4 v154, v[76:79], s[100:101] offset:64 sc1
	global_store_dwordx4 v154, v[68:71], s[100:101] offset:512 sc1
	global_store_dwordx4 v154, v[64:67], s[100:101] offset:576 sc1
	v_add_u32_e32 v154, 128, v152
	v_lshl_add_u32 v154, v154, 13, v153
	global_load_dwordx4 v[178:181], v154, s[100:101] offset:0
	global_load_dwordx4 v[182:185], v154, s[100:101] offset:64
	global_load_dwordx4 v[186:189], v154, s[100:101] offset:512
	global_load_dwordx4 v[190:193], v154, s[100:101] offset:576
	v_add_u32_e32 v154, 144, v152
	v_lshl_add_u32 v154, v154, 13, v153
	global_load_dwordx4 v[194:197], v154, s[100:101] offset:0
	global_load_dwordx4 v[198:201], v154, s[100:101] offset:64
	global_load_dwordx4 v[202:205], v154, s[100:101] offset:512
	global_load_dwordx4 v[206:209], v154, s[100:101] offset:576
	v_add_u32_e32 v154, 160, v152
	v_lshl_add_u32 v154, v154, 13, v153
	global_load_dwordx4 v[210:213], v154, s[100:101] offset:0
	global_load_dwordx4 v[232:235], v154, s[100:101] offset:64
	global_load_dwordx4 v[236:239], v154, s[100:101] offset:512
	global_load_dwordx4 v[240:243], v154, s[100:101] offset:576
	v_add_u32_e32 v154, 176, v152
	v_lshl_add_u32 v154, v154, 13, v153
	global_load_dwordx4 v[244:247], v154, s[100:101] offset:0
	global_load_dwordx4 v[248:251], v154, s[100:101] offset:64
	global_load_dwordx4 v[162:165], v154, s[100:101] offset:512
	global_load_dwordx4 v[166:169], v154, s[100:101] offset:576
	s_waitcnt vmcnt(0)
	v_pk_fma_f32 v[60:61], v[60:61], v[128:129], v[178:179]
	v_pk_fma_f32 v[62:63], v[62:63], v[130:131], v[180:181]
	v_pk_fma_f32 v[56:57], v[56:57], v[132:133], v[182:183]
	v_pk_fma_f32 v[58:59], v[58:59], v[134:135], v[184:185]
	v_pk_fma_f32 v[48:49], v[48:49], v[136:137], v[186:187]
	v_pk_fma_f32 v[50:51], v[50:51], v[138:139], v[188:189]
	v_pk_fma_f32 v[40:41], v[40:41], v[140:141], v[190:191]
	v_pk_fma_f32 v[42:43], v[42:43], v[142:143], v[192:193]
	v_pk_fma_f32 v[52:53], v[52:53], v[128:129], v[194:195]
	v_pk_fma_f32 v[54:55], v[54:55], v[130:131], v[196:197]
	v_pk_fma_f32 v[44:45], v[44:45], v[132:133], v[198:199]
	v_pk_fma_f32 v[46:47], v[46:47], v[134:135], v[200:201]
	v_pk_fma_f32 v[32:33], v[32:33], v[136:137], v[202:203]
	v_pk_fma_f32 v[34:35], v[34:35], v[138:139], v[204:205]
	v_pk_fma_f32 v[24:25], v[24:25], v[140:141], v[206:207]
	v_pk_fma_f32 v[26:27], v[26:27], v[142:143], v[208:209]
	v_pk_fma_f32 v[36:37], v[36:37], v[128:129], v[210:211]
	v_pk_fma_f32 v[38:39], v[38:39], v[130:131], v[212:213]
	v_pk_fma_f32 v[28:29], v[28:29], v[132:133], v[232:233]
	v_pk_fma_f32 v[30:31], v[30:31], v[134:135], v[234:235]
	v_pk_fma_f32 v[20:21], v[20:21], v[136:137], v[236:237]
	v_pk_fma_f32 v[22:23], v[22:23], v[138:139], v[238:239]
	v_pk_fma_f32 v[12:13], v[12:13], v[140:141], v[240:241]
	v_pk_fma_f32 v[14:15], v[14:15], v[142:143], v[242:243]
	v_pk_fma_f32 v[16:17], v[16:17], v[128:129], v[244:245]
	v_pk_fma_f32 v[18:19], v[18:19], v[130:131], v[246:247]
	v_pk_fma_f32 v[8:9], v[8:9], v[132:133], v[248:249]
	v_pk_fma_f32 v[10:11], v[10:11], v[134:135], v[250:251]
	v_pk_fma_f32 v[4:5], v[4:5], v[136:137], v[162:163]
	v_pk_fma_f32 v[6:7], v[6:7], v[138:139], v[164:165]
	v_pk_fma_f32 v[0:1], v[0:1], v[140:141], v[166:167]
	v_pk_fma_f32 v[2:3], v[2:3], v[142:143], v[168:169]
	v_add_u32_e32 v154, 128, v152
	v_lshl_add_u32 v154, v154, 13, v153
	global_store_dwordx4 v154, v[60:63], s[100:101] offset:0 sc1
	global_store_dwordx4 v154, v[56:59], s[100:101] offset:64 sc1
	global_store_dwordx4 v154, v[48:51], s[100:101] offset:512 sc1
	global_store_dwordx4 v154, v[40:43], s[100:101] offset:576 sc1
	v_add_u32_e32 v154, 144, v152
	v_lshl_add_u32 v154, v154, 13, v153
	global_store_dwordx4 v154, v[52:55], s[100:101] offset:0 sc1
	global_store_dwordx4 v154, v[44:47], s[100:101] offset:64 sc1
	global_store_dwordx4 v154, v[32:35], s[100:101] offset:512 sc1
	global_store_dwordx4 v154, v[24:27], s[100:101] offset:576 sc1
	v_add_u32_e32 v154, 160, v152
	v_lshl_add_u32 v154, v154, 13, v153
	global_store_dwordx4 v154, v[36:39], s[100:101] offset:0 sc1
	global_store_dwordx4 v154, v[28:31], s[100:101] offset:64 sc1
	global_store_dwordx4 v154, v[20:23], s[100:101] offset:512 sc1
	global_store_dwordx4 v154, v[12:15], s[100:101] offset:576 sc1
	v_add_u32_e32 v154, 176, v152
	v_lshl_add_u32 v154, v154, 13, v153
	global_store_dwordx4 v154, v[16:19], s[100:101] offset:0 sc1
	global_store_dwordx4 v154, v[8:11], s[100:101] offset:64 sc1
	global_store_dwordx4 v154, v[4:7], s[100:101] offset:512 sc1
	global_store_dwordx4 v154, v[0:3], s[100:101] offset:576 sc1
	v_readlane_b32 s26, v253, 21
	v_readlane_b32 s27, v253, 22
	s_add_u32 s26, s26, 0x2000
	s_addc_u32 s27, s27, 0
	global_load_dwordx4 v[128:131], v153, s[26:27] offset:0
	global_load_dwordx4 v[132:135], v153, s[26:27] offset:64
	global_load_dwordx4 v[136:139], v153, s[26:27] offset:512
	global_load_dwordx4 v[140:143], v153, s[26:27] offset:576
	s_add_u32 s26, s24, 0x4000
	s_addc_u32 s27, s25, 0
	global_load_dwordx4 v[232:235], v153, s[26:27] offset:0
	global_load_dwordx4 v[236:239], v153, s[26:27] offset:64
	global_load_dwordx4 v[240:243], v153, s[26:27] offset:512
	global_load_dwordx4 v[244:247], v153, s[26:27] offset:576
	s_add_u32 s26, s24, 0x2000
	s_addc_u32 s27, s25, 0
	global_load_dwordx4 v[162:165], v153, s[26:27] offset:0
	global_load_dwordx4 v[166:169], v153, s[26:27] offset:64
	global_load_dwordx4 v[170:173], v153, s[26:27] offset:512
	global_load_dwordx4 v[248:251], v153, s[26:27] offset:576
	v_mul_f32_e32 v178, v124, v124
	v_fmac_f32_e32 v178, v125, v125
	v_fmac_f32_e32 v178, v126, v126
	v_fmac_f32_e32 v178, v127, v127
	v_fmac_f32_e32 v178, v120, v120
	v_fmac_f32_e32 v178, v121, v121
	v_fmac_f32_e32 v178, v122, v122
	v_fmac_f32_e32 v178, v123, v123
	v_fmac_f32_e32 v178, v116, v116
	v_fmac_f32_e32 v178, v117, v117
	v_fmac_f32_e32 v178, v118, v118
	v_fmac_f32_e32 v178, v119, v119
	v_fmac_f32_e32 v178, v104, v104
	v_fmac_f32_e32 v178, v105, v105
	v_fmac_f32_e32 v178, v106, v106
	v_fmac_f32_e32 v178, v107, v107
	v_mul_f32_e32 v179, v112, v112
	v_fmac_f32_e32 v179, v113, v113
	v_fmac_f32_e32 v179, v114, v114
	v_fmac_f32_e32 v179, v115, v115
	v_fmac_f32_e32 v179, v108, v108
	v_fmac_f32_e32 v179, v109, v109
	v_fmac_f32_e32 v179, v110, v110
	v_fmac_f32_e32 v179, v111, v111
	v_fmac_f32_e32 v179, v96, v96
	v_fmac_f32_e32 v179, v97, v97
	v_fmac_f32_e32 v179, v98, v98
	v_fmac_f32_e32 v179, v99, v99
	v_fmac_f32_e32 v179, v88, v88
	v_fmac_f32_e32 v179, v89, v89
	v_fmac_f32_e32 v179, v90, v90
	v_fmac_f32_e32 v179, v91, v91
	v_mul_f32_e32 v180, v100, v100
	v_fmac_f32_e32 v180, v101, v101
	v_fmac_f32_e32 v180, v102, v102
	v_fmac_f32_e32 v180, v103, v103
	v_fmac_f32_e32 v180, v92, v92
	v_fmac_f32_e32 v180, v93, v93
	v_fmac_f32_e32 v180, v94, v94
	v_fmac_f32_e32 v180, v95, v95
	v_fmac_f32_e32 v180, v80, v80
	v_fmac_f32_e32 v180, v81, v81
	v_fmac_f32_e32 v180, v82, v82
	v_fmac_f32_e32 v180, v83, v83
	v_fmac_f32_e32 v180, v72, v72
	v_fmac_f32_e32 v180, v73, v73
	v_fmac_f32_e32 v180, v74, v74
	v_fmac_f32_e32 v180, v75, v75
	v_mul_f32_e32 v181, v84, v84
	v_fmac_f32_e32 v181, v85, v85
	v_fmac_f32_e32 v181, v86, v86
	v_fmac_f32_e32 v181, v87, v87
	v_fmac_f32_e32 v181, v76, v76
	v_fmac_f32_e32 v181, v77, v77
	v_fmac_f32_e32 v181, v78, v78
	v_fmac_f32_e32 v181, v79, v79
	v_fmac_f32_e32 v181, v68, v68
	v_fmac_f32_e32 v181, v69, v69
	v_fmac_f32_e32 v181, v70, v70
	v_fmac_f32_e32 v181, v71, v71
	v_fmac_f32_e32 v181, v64, v64
	v_fmac_f32_e32 v181, v65, v65
	v_fmac_f32_e32 v181, v66, v66
	v_fmac_f32_e32 v181, v67, v67
	v_mul_f32_e32 v182, v60, v60
	v_fmac_f32_e32 v182, v61, v61
	v_fmac_f32_e32 v182, v62, v62
	v_fmac_f32_e32 v182, v63, v63
	v_fmac_f32_e32 v182, v56, v56
	v_fmac_f32_e32 v182, v57, v57
	v_fmac_f32_e32 v182, v58, v58
	v_fmac_f32_e32 v182, v59, v59
	v_fmac_f32_e32 v182, v48, v48
	v_fmac_f32_e32 v182, v49, v49
	v_fmac_f32_e32 v182, v50, v50
	v_fmac_f32_e32 v182, v51, v51
	v_fmac_f32_e32 v182, v40, v40
	v_fmac_f32_e32 v182, v41, v41
	v_fmac_f32_e32 v182, v42, v42
	v_fmac_f32_e32 v182, v43, v43
	v_mul_f32_e32 v183, v52, v52
	v_fmac_f32_e32 v183, v53, v53
	v_fmac_f32_e32 v183, v54, v54
	v_fmac_f32_e32 v183, v55, v55
	v_fmac_f32_e32 v183, v44, v44
	v_fmac_f32_e32 v183, v45, v45
	v_fmac_f32_e32 v183, v46, v46
	v_fmac_f32_e32 v183, v47, v47
	v_fmac_f32_e32 v183, v32, v32
	v_fmac_f32_e32 v183, v33, v33
	v_fmac_f32_e32 v183, v34, v34
	v_fmac_f32_e32 v183, v35, v35
	v_fmac_f32_e32 v183, v24, v24
	v_fmac_f32_e32 v183, v25, v25
	v_fmac_f32_e32 v183, v26, v26
	v_fmac_f32_e32 v183, v27, v27
	v_mul_f32_e32 v184, v36, v36
	v_fmac_f32_e32 v184, v37, v37
	v_fmac_f32_e32 v184, v38, v38
	v_fmac_f32_e32 v184, v39, v39
	v_fmac_f32_e32 v184, v28, v28
	v_fmac_f32_e32 v184, v29, v29
	v_fmac_f32_e32 v184, v30, v30
	v_fmac_f32_e32 v184, v31, v31
	v_fmac_f32_e32 v184, v20, v20
	v_fmac_f32_e32 v184, v21, v21
	v_fmac_f32_e32 v184, v22, v22
	v_fmac_f32_e32 v184, v23, v23
	v_fmac_f32_e32 v184, v12, v12
	v_fmac_f32_e32 v184, v13, v13
	v_fmac_f32_e32 v184, v14, v14
	v_fmac_f32_e32 v184, v15, v15
	v_mul_f32_e32 v185, v16, v16
	v_fmac_f32_e32 v185, v17, v17
	v_fmac_f32_e32 v185, v18, v18
	v_fmac_f32_e32 v185, v19, v19
	v_fmac_f32_e32 v185, v8, v8
	v_fmac_f32_e32 v185, v9, v9
	v_fmac_f32_e32 v185, v10, v10
	v_fmac_f32_e32 v185, v11, v11
	v_fmac_f32_e32 v185, v4, v4
	v_fmac_f32_e32 v185, v5, v5
	v_fmac_f32_e32 v185, v6, v6
	v_fmac_f32_e32 v185, v7, v7
	v_fmac_f32_e32 v185, v0, v0
	v_fmac_f32_e32 v185, v1, v1
	v_fmac_f32_e32 v185, v2, v2
	v_fmac_f32_e32 v185, v3, v3
	v_mov_b32_e32 v186, v178
	v_mov_b32_e32 v187, v179
	v_mov_b32_e32 v188, v180
	v_mov_b32_e32 v189, v181
	v_mov_b32_e32 v190, v182
	v_mov_b32_e32 v191, v183
	v_mov_b32_e32 v192, v184
	v_mov_b32_e32 v193, v185
	s_nop 1
	v_permlane32_swap_b32_e32 v178, v186
	v_permlane32_swap_b32_e32 v179, v187
	v_permlane32_swap_b32_e32 v180, v188
	v_permlane32_swap_b32_e32 v181, v189
	v_permlane32_swap_b32_e32 v182, v190
	v_permlane32_swap_b32_e32 v183, v191
	v_permlane32_swap_b32_e32 v184, v192
	v_permlane32_swap_b32_e32 v185, v193
	s_nop 1
	v_add_f32_e32 v178, v178, v186
	v_add_f32_e32 v179, v179, v187
	v_add_f32_e32 v180, v180, v188
	v_add_f32_e32 v181, v181, v189
	v_add_f32_e32 v182, v182, v190
	v_add_f32_e32 v183, v183, v191
	v_add_f32_e32 v184, v184, v192
	v_add_f32_e32 v185, v185, v193
	v_mov_b32_e32 v186, v178
	v_mov_b32_e32 v187, v179
	v_mov_b32_e32 v188, v180
	v_mov_b32_e32 v189, v181
	v_mov_b32_e32 v190, v182
	v_mov_b32_e32 v191, v183
	v_mov_b32_e32 v192, v184
	v_mov_b32_e32 v193, v185
	s_nop 1
	v_permlane16_swap_b32_e32 v178, v186
	v_permlane16_swap_b32_e32 v179, v187
	v_permlane16_swap_b32_e32 v180, v188
	v_permlane16_swap_b32_e32 v181, v189
	v_permlane16_swap_b32_e32 v182, v190
	v_permlane16_swap_b32_e32 v183, v191
	v_permlane16_swap_b32_e32 v184, v192
	v_permlane16_swap_b32_e32 v185, v193
	s_nop 1
	v_add_f32_e32 v178, v178, v186
	v_add_f32_e32 v179, v179, v187
	v_add_f32_e32 v180, v180, v188
	v_add_f32_e32 v181, v181, v189
	v_add_f32_e32 v182, v182, v190
	v_add_f32_e32 v183, v183, v191
	v_add_f32_e32 v184, v184, v192
	v_add_f32_e32 v185, v185, v193
	v_and_b32_e32 v156, 15, v152
	s_lshr_b32 s28, s94, 6
	s_lshl_b32 s28, s28, 2
	s_lshr_b32 s29, s95, 5
	s_add_i32 s28, s28, s29
	s_lshl_b32 s28, s28, 9
	s_add_i32 s28, s28, 0x20000
	v_lshl_add_u32 v154, v156, 2, s28
	ds_write_b32 v154, v178 offset:0
	ds_write_b32 v154, v179 offset:64
	ds_write_b32 v154, v180 offset:128
	ds_write_b32 v154, v181 offset:192
	ds_write_b32 v154, v182 offset:256
	ds_write_b32 v154, v183 offset:320
	ds_write_b32 v154, v184 offset:384
	ds_write_b32 v154, v185 offset:448
	s_waitcnt lgkmcnt(0)
	s_barrier
	s_lshr_b32 s28, s94, 6
	s_lshl_b32 s28, s28, 11
	s_add_i32 s28, s28, 0x20000
	v_lshl_add_u32 v154, v156, 2, s28
	ds_read_b32 v194, v154 offset:0
	ds_read_b32 v195, v154 offset:512
	ds_read_b32 v196, v154 offset:1024
	ds_read_b32 v197, v154 offset:1536
	ds_read_b32 v198, v154 offset:64
	ds_read_b32 v199, v154 offset:576
	ds_read_b32 v200, v154 offset:1088
	ds_read_b32 v201, v154 offset:1600
	ds_read_b32 v202, v154 offset:128
	ds_read_b32 v203, v154 offset:640
	ds_read_b32 v204, v154 offset:1152
	ds_read_b32 v205, v154 offset:1664
	ds_read_b32 v206, v154 offset:192
	ds_read_b32 v207, v154 offset:704
	ds_read_b32 v208, v154 offset:1216
	ds_read_b32 v209, v154 offset:1728
	s_waitcnt lgkmcnt(0)
	v_add_f32_e32 v178, v194, v195
	v_add_f32_e32 v178, v178, v196
	v_add_f32_e32 v178, v178, v197
	v_add_f32_e32 v179, v198, v199
	v_add_f32_e32 v179, v179, v200
	v_add_f32_e32 v179, v179, v201
	v_add_f32_e32 v180, v202, v203
	v_add_f32_e32 v180, v180, v204
	v_add_f32_e32 v180, v180, v205
	v_add_f32_e32 v181, v206, v207
	v_add_f32_e32 v181, v181, v208
	v_add_f32_e32 v181, v181, v209
	ds_read_b32 v194, v154 offset:256
	ds_read_b32 v195, v154 offset:768
	ds_read_b32 v196, v154 offset:1280
	ds_read_b32 v197, v154 offset:1792
	ds_read_b32 v198, v154 offset:320
	ds_read_b32 v199, v154 offset:832
	ds_read_b32 v200, v154 offset:1344
	ds_read_b32 v201, v154 offset:1856
	ds_read_b32 v202, v154 offset:384
	ds_read_b32 v203, v154 offset:896
	ds_read_b32 v204, v154 offset:1408
	ds_read_b32 v205, v154 offset:1920
	ds_read_b32 v206, v154 offset:448
	ds_read_b32 v207, v154 offset:960
	ds_read_b32 v208, v154 offset:1472
	ds_read_b32 v209, v154 offset:1984
	s_waitcnt lgkmcnt(0)
	v_add_f32_e32 v182, v194, v195
	v_add_f32_e32 v182, v182, v196
	v_add_f32_e32 v182, v182, v197
	v_add_f32_e32 v183, v198, v199
	v_add_f32_e32 v183, v183, v200
	v_add_f32_e32 v183, v183, v201
	v_add_f32_e32 v184, v202, v203
	v_add_f32_e32 v184, v184, v204
	v_add_f32_e32 v184, v184, v205
	v_add_f32_e32 v185, v206, v207
	v_add_f32_e32 v185, v185, v208
	v_add_f32_e32 v185, v185, v209
	v_readlane_b32 s100, v254, 48
	v_readlane_b32 s101, v254, 49
	s_add_u32 s100, s100, 0x90000
	s_addc_u32 s101, s101, 0
	s_cmp_lg_u32 s95, 0
	s_cbranch_scc1 .Lf7_nopub
	s_mul_i32 s28, s17, 0x2400
	v_add_u32_e32 v154, s28, v152
	v_lshlrev_b32_e32 v154, 2, v154
	global_store_dword v154, v178, s[100:101] offset:0 sc1
	global_store_dword v154, v179, s[100:101] offset:64 sc1
	global_store_dword v154, v180, s[100:101] offset:128 sc1
	global_store_dword v154, v181, s[100:101] offset:192 sc1
	global_store_dword v154, v182, s[100:101] offset:512 sc1
	global_store_dword v154, v183, s[100:101] offset:576 sc1
	global_store_dword v154, v184, s[100:101] offset:640 sc1
	global_store_dword v154, v185, s[100:101] offset:704 sc1
.Lf7_nopub:
	s_waitcnt vmcnt(0)
	s_barrier
	s_mov_b64 s[20:21], exec
	v_cmp_eq_u32_e32 vcc, 0, v214
	s_and_b64 exec, exec, vcc
	s_cbranch_execz .Lf7_synced
	s_lshl_b32 s28, s16, 2
	s_add_i32 s28, s28, 0x50100
	v_mov_b32_e32 v154, s28
	v_mov_b32_e32 v155, 1
	global_atomic_add v154, v155, s[100:101]
	s_mov_b32 s29, 0
.Lf7_poll:
	s_sleep 1
	global_load_dword v155, v154, s[100:101] sc1
	s_waitcnt vmcnt(0)
	s_nop 0
	v_readfirstlane_b32 s28, v155
	s_add_i32 s29, s29, 1
	s_cmp_ge_u32 s28, 8
	s_cbranch_scc1 .Lf7_synced
	s_cmp_lt_u32 s29, 0x400000
	s_cbranch_scc1 .Lf7_poll
.Lf7_synced:
	s_mov_b64 exec, s[20:21]
	s_barrier
	v_bfe_u32 v157, v153, 4, 2
	v_mul_u32_u24_e32 v154, 0x4800, v157
	v_add_u32_e32 v154, v154, v152
	v_lshlrev_b32_e32 v154, 2, v154
	v_add_u32_e32 v155, 0x9000, v154
	global_load_dword v194, v154, s[100:101] offset:0 sc1
	global_load_dword v195, v155, s[100:101] offset:0 sc1
	global_load_dword v196, v154, s[100:101] offset:64 sc1
	global_load_dword v197, v155, s[100:101] offset:64 sc1
	global_load_dword v198, v154, s[100:101] offset:128 sc1
	global_load_dword v199, v155, s[100:101] offset:128 sc1
	global_load_dword v200, v154, s[100:101] offset:192 sc1
	global_load_dword v201, v155, s[100:101] offset:192 sc1
	global_load_dword v202, v154, s[100:101] offset:512 sc1
	global_load_dword v203, v155, s[100:101] offset:512 sc1
	global_load_dword v204, v154, s[100:101] offset:576 sc1
	global_load_dword v205, v155, s[100:101] offset:576 sc1
	global_load_dword v206, v154, s[100:101] offset:640 sc1
	global_load_dword v207, v155, s[100:101] offset:640 sc1
	global_load_dword v208, v154, s[100:101] offset:704 sc1
	global_load_dword v209, v155, s[100:101] offset:704 sc1
	s_waitcnt vmcnt(0)
	v_add_f32_e32 v178, v194, v195
	v_add_f32_e32 v179, v196, v197
	v_add_f32_e32 v180, v198, v199
	v_add_f32_e32 v181, v200, v201
	v_add_f32_e32 v182, v202, v203
	v_add_f32_e32 v183, v204, v205
	v_add_f32_e32 v184, v206, v207
	v_add_f32_e32 v185, v208, v209
	v_mov_b32_e32 v186, v178
	v_mov_b32_e32 v187, v179
	v_mov_b32_e32 v188, v180
	v_mov_b32_e32 v189, v181
	v_mov_b32_e32 v190, v182
	v_mov_b32_e32 v191, v183
	v_mov_b32_e32 v192, v184
	v_mov_b32_e32 v193, v185
	s_nop 1
	v_permlane32_swap_b32_e32 v178, v186
	v_permlane32_swap_b32_e32 v179, v187
	v_permlane32_swap_b32_e32 v180, v188
	v_permlane32_swap_b32_e32 v181, v189
	v_permlane32_swap_b32_e32 v182, v190
	v_permlane32_swap_b32_e32 v183, v191
	v_permlane32_swap_b32_e32 v184, v192
	v_permlane32_swap_b32_e32 v185, v193
	s_nop 1
	v_add_f32_e32 v178, v178, v186
	v_add_f32_e32 v179, v179, v187
	v_add_f32_e32 v180, v180, v188
	v_add_f32_e32 v181, v181, v189
	v_add_f32_e32 v182, v182, v190
	v_add_f32_e32 v183, v183, v191
	v_add_f32_e32 v184, v184, v192
	v_add_f32_e32 v185, v185, v193
	v_mov_b32_e32 v186, v178
	v_mov_b32_e32 v187, v179
	v_mov_b32_e32 v188, v180
	v_mov_b32_e32 v189, v181
	v_mov_b32_e32 v190, v182
	v_mov_b32_e32 v191, v183
	v_mov_b32_e32 v192, v184
	v_mov_b32_e32 v193, v185
	s_nop 1
	v_permlane16_swap_b32_e32 v178, v186
	v_permlane16_swap_b32_e32 v179, v187
	v_permlane16_swap_b32_e32 v180, v188
	v_permlane16_swap_b32_e32 v181, v189
	v_permlane16_swap_b32_e32 v182, v190
	v_permlane16_swap_b32_e32 v183, v191
	v_permlane16_swap_b32_e32 v184, v192
	v_permlane16_swap_b32_e32 v185, v193
	s_nop 1
	v_add_f32_e32 v178, v178, v186
	v_add_f32_e32 v179, v179, v187
	v_add_f32_e32 v180, v180, v188
	v_add_f32_e32 v181, v181, v189
	v_add_f32_e32 v182, v182, v190
	v_add_f32_e32 v183, v183, v191
	v_add_f32_e32 v184, v184, v192
	v_add_f32_e32 v185, v185, v193
	v_mov_b32_e32 v222, 0x358637bd
	v_mov_b32_e32 v223, 0x260
	v_fmamk_f32 v178, v178, 0x3a000000, v222
	v_mul_f32_e32 v211, 0x4f800000, v178
	v_cmp_gt_f32_e32 vcc, 0xf800000, v178
	s_nop 1
	v_cndmask_b32_e32 v210, v178, v211, vcc
	v_sqrt_f32_e32 v211, v210
	s_nop 0
	v_add_u32_e32 v212, -1, v211
	v_fma_f32 v213, -v212, v211, v210
	v_cmp_ge_f32_e64 s[26:27], 0, v213
	v_add_u32_e32 v213, 1, v211
	s_nop 0
	v_cndmask_b32_e64 v212, v211, v212, s[26:27]
	v_fma_f32 v211, -v213, v211, v210
	v_cmp_lt_f32_e64 s[26:27], 0, v211
	s_nop 1
	v_cndmask_b32_e64 v211, v212, v213, s[26:27]
	v_mul_f32_e32 v212, 0x37800000, v211
	v_cndmask_b32_e32 v211, v211, v212, vcc
	v_cmp_class_f32_e32 vcc, v210, v223
	s_nop 1
	v_cndmask_b32_e32 v210, v211, v210, vcc
	v_div_scale_f32 v211, s[26:27], v210, v210, 1.0
	v_rcp_f32_e32 v212, v211
	s_nop 1
	v_fma_f32 v213, -v211, v212, 1.0
	v_fmac_f32_e32 v212, v213, v212
	v_div_scale_f32 v213, vcc, 1.0, v210, 1.0
	v_mul_f32_e32 v220, v213, v212
	v_fma_f32 v221, -v211, v220, v213
	v_fmac_f32_e32 v220, v221, v212
	v_fma_f32 v211, -v211, v220, v213
	s_nop 0
	v_div_fmas_f32 v211, v211, v212, v220
	v_div_fixup_f32 v194, v211, v210, 1.0
	v_fmamk_f32 v179, v179, 0x3a000000, v222
	v_mul_f32_e32 v211, 0x4f800000, v179
	v_cmp_gt_f32_e32 vcc, 0xf800000, v179
	s_nop 1
	v_cndmask_b32_e32 v210, v179, v211, vcc
	v_sqrt_f32_e32 v211, v210
	s_nop 0
	v_add_u32_e32 v212, -1, v211
	v_fma_f32 v213, -v212, v211, v210
	v_cmp_ge_f32_e64 s[26:27], 0, v213
	v_add_u32_e32 v213, 1, v211
	s_nop 0
	v_cndmask_b32_e64 v212, v211, v212, s[26:27]
	v_fma_f32 v211, -v213, v211, v210
	v_cmp_lt_f32_e64 s[26:27], 0, v211
	s_nop 1
	v_cndmask_b32_e64 v211, v212, v213, s[26:27]
	v_mul_f32_e32 v212, 0x37800000, v211
	v_cndmask_b32_e32 v211, v211, v212, vcc
	v_cmp_class_f32_e32 vcc, v210, v223
	s_nop 1
	v_cndmask_b32_e32 v210, v211, v210, vcc
	v_div_scale_f32 v211, s[26:27], v210, v210, 1.0
	v_rcp_f32_e32 v212, v211
	s_nop 1
	v_fma_f32 v213, -v211, v212, 1.0
	v_fmac_f32_e32 v212, v213, v212
	v_div_scale_f32 v213, vcc, 1.0, v210, 1.0
	v_mul_f32_e32 v220, v213, v212
	v_fma_f32 v221, -v211, v220, v213
	v_fmac_f32_e32 v220, v221, v212
	v_fma_f32 v211, -v211, v220, v213
	s_nop 0
	v_div_fmas_f32 v211, v211, v212, v220
	v_div_fixup_f32 v196, v211, v210, 1.0
	v_fmamk_f32 v180, v180, 0x3a000000, v222
	v_mul_f32_e32 v211, 0x4f800000, v180
	v_cmp_gt_f32_e32 vcc, 0xf800000, v180
	s_nop 1
	v_cndmask_b32_e32 v210, v180, v211, vcc
	v_sqrt_f32_e32 v211, v210
	s_nop 0
	v_add_u32_e32 v212, -1, v211
	v_fma_f32 v213, -v212, v211, v210
	v_cmp_ge_f32_e64 s[26:27], 0, v213
	v_add_u32_e32 v213, 1, v211
	s_nop 0
	v_cndmask_b32_e64 v212, v211, v212, s[26:27]
	v_fma_f32 v211, -v213, v211, v210
	v_cmp_lt_f32_e64 s[26:27], 0, v211
	s_nop 1
	v_cndmask_b32_e64 v211, v212, v213, s[26:27]
	v_mul_f32_e32 v212, 0x37800000, v211
	v_cndmask_b32_e32 v211, v211, v212, vcc
	v_cmp_class_f32_e32 vcc, v210, v223
	s_nop 1
	v_cndmask_b32_e32 v210, v211, v210, vcc
	v_div_scale_f32 v211, s[26:27], v210, v210, 1.0
	v_rcp_f32_e32 v212, v211
	s_nop 1
	v_fma_f32 v213, -v211, v212, 1.0
	v_fmac_f32_e32 v212, v213, v212
	v_div_scale_f32 v213, vcc, 1.0, v210, 1.0
	v_mul_f32_e32 v220, v213, v212
	v_fma_f32 v221, -v211, v220, v213
	v_fmac_f32_e32 v220, v221, v212
	v_fma_f32 v211, -v211, v220, v213
	s_nop 0
	v_div_fmas_f32 v211, v211, v212, v220
	v_div_fixup_f32 v198, v211, v210, 1.0
	v_fmamk_f32 v181, v181, 0x3a000000, v222
	v_mul_f32_e32 v211, 0x4f800000, v181
	v_cmp_gt_f32_e32 vcc, 0xf800000, v181
	s_nop 1
	v_cndmask_b32_e32 v210, v181, v211, vcc
	v_sqrt_f32_e32 v211, v210
	s_nop 0
	v_add_u32_e32 v212, -1, v211
	v_fma_f32 v213, -v212, v211, v210
	v_cmp_ge_f32_e64 s[26:27], 0, v213
	v_add_u32_e32 v213, 1, v211
	s_nop 0
	v_cndmask_b32_e64 v212, v211, v212, s[26:27]
	v_fma_f32 v211, -v213, v211, v210
	v_cmp_lt_f32_e64 s[26:27], 0, v211
	s_nop 1
	v_cndmask_b32_e64 v211, v212, v213, s[26:27]
	v_mul_f32_e32 v212, 0x37800000, v211
	v_cndmask_b32_e32 v211, v211, v212, vcc
	v_cmp_class_f32_e32 vcc, v210, v223
	s_nop 1
	v_cndmask_b32_e32 v210, v211, v210, vcc
	v_div_scale_f32 v211, s[26:27], v210, v210, 1.0
	v_rcp_f32_e32 v212, v211
	s_nop 1
	v_fma_f32 v213, -v211, v212, 1.0
	v_fmac_f32_e32 v212, v213, v212
	v_div_scale_f32 v213, vcc, 1.0, v210, 1.0
	v_mul_f32_e32 v220, v213, v212
	v_fma_f32 v221, -v211, v220, v213
	v_fmac_f32_e32 v220, v221, v212
	v_fma_f32 v211, -v211, v220, v213
	s_nop 0
	v_div_fmas_f32 v211, v211, v212, v220
	v_div_fixup_f32 v200, v211, v210, 1.0
	v_fmamk_f32 v182, v182, 0x3a000000, v222
	v_mul_f32_e32 v211, 0x4f800000, v182
	v_cmp_gt_f32_e32 vcc, 0xf800000, v182
	s_nop 1
	v_cndmask_b32_e32 v210, v182, v211, vcc
	v_sqrt_f32_e32 v211, v210
	s_nop 0
	v_add_u32_e32 v212, -1, v211
	v_fma_f32 v213, -v212, v211, v210
	v_cmp_ge_f32_e64 s[26:27], 0, v213
	v_add_u32_e32 v213, 1, v211
	s_nop 0
	v_cndmask_b32_e64 v212, v211, v212, s[26:27]
	v_fma_f32 v211, -v213, v211, v210
	v_cmp_lt_f32_e64 s[26:27], 0, v211
	s_nop 1
	v_cndmask_b32_e64 v211, v212, v213, s[26:27]
	v_mul_f32_e32 v212, 0x37800000, v211
	v_cndmask_b32_e32 v211, v211, v212, vcc
	v_cmp_class_f32_e32 vcc, v210, v223
	s_nop 1
	v_cndmask_b32_e32 v210, v211, v210, vcc
	v_div_scale_f32 v211, s[26:27], v210, v210, 1.0
	v_rcp_f32_e32 v212, v211
	s_nop 1
	v_fma_f32 v213, -v211, v212, 1.0
	v_fmac_f32_e32 v212, v213, v212
	v_div_scale_f32 v213, vcc, 1.0, v210, 1.0
	v_mul_f32_e32 v220, v213, v212
	v_fma_f32 v221, -v211, v220, v213
	v_fmac_f32_e32 v220, v221, v212
	v_fma_f32 v211, -v211, v220, v213
	s_nop 0
	v_div_fmas_f32 v211, v211, v212, v220
	v_div_fixup_f32 v202, v211, v210, 1.0
	v_fmamk_f32 v183, v183, 0x3a000000, v222
	v_mul_f32_e32 v211, 0x4f800000, v183
	v_cmp_gt_f32_e32 vcc, 0xf800000, v183
	s_nop 1
	v_cndmask_b32_e32 v210, v183, v211, vcc
	v_sqrt_f32_e32 v211, v210
	s_nop 0
	v_add_u32_e32 v212, -1, v211
	v_fma_f32 v213, -v212, v211, v210
	v_cmp_ge_f32_e64 s[26:27], 0, v213
	v_add_u32_e32 v213, 1, v211
	s_nop 0
	v_cndmask_b32_e64 v212, v211, v212, s[26:27]
	v_fma_f32 v211, -v213, v211, v210
	v_cmp_lt_f32_e64 s[26:27], 0, v211
	s_nop 1
	v_cndmask_b32_e64 v211, v212, v213, s[26:27]
	v_mul_f32_e32 v212, 0x37800000, v211
	v_cndmask_b32_e32 v211, v211, v212, vcc
	v_cmp_class_f32_e32 vcc, v210, v223
	s_nop 1
	v_cndmask_b32_e32 v210, v211, v210, vcc
	v_div_scale_f32 v211, s[26:27], v210, v210, 1.0
	v_rcp_f32_e32 v212, v211
	s_nop 1
	v_fma_f32 v213, -v211, v212, 1.0
	v_fmac_f32_e32 v212, v213, v212
	v_div_scale_f32 v213, vcc, 1.0, v210, 1.0
	v_mul_f32_e32 v220, v213, v212
	v_fma_f32 v221, -v211, v220, v213
	v_fmac_f32_e32 v220, v221, v212
	v_fma_f32 v211, -v211, v220, v213
	s_nop 0
	v_div_fmas_f32 v211, v211, v212, v220
	v_div_fixup_f32 v204, v211, v210, 1.0
	v_fmamk_f32 v184, v184, 0x3a000000, v222
	v_mul_f32_e32 v211, 0x4f800000, v184
	v_cmp_gt_f32_e32 vcc, 0xf800000, v184
	s_nop 1
	v_cndmask_b32_e32 v210, v184, v211, vcc
	v_sqrt_f32_e32 v211, v210
	s_nop 0
	v_add_u32_e32 v212, -1, v211
	v_fma_f32 v213, -v212, v211, v210
	v_cmp_ge_f32_e64 s[26:27], 0, v213
	v_add_u32_e32 v213, 1, v211
	s_nop 0
	v_cndmask_b32_e64 v212, v211, v212, s[26:27]
	v_fma_f32 v211, -v213, v211, v210
	v_cmp_lt_f32_e64 s[26:27], 0, v211
	s_nop 1
	v_cndmask_b32_e64 v211, v212, v213, s[26:27]
	v_mul_f32_e32 v212, 0x37800000, v211
	v_cndmask_b32_e32 v211, v211, v212, vcc
	v_cmp_class_f32_e32 vcc, v210, v223
	s_nop 1
	v_cndmask_b32_e32 v210, v211, v210, vcc
	v_div_scale_f32 v211, s[26:27], v210, v210, 1.0
	v_rcp_f32_e32 v212, v211
	s_nop 1
	v_fma_f32 v213, -v211, v212, 1.0
	v_fmac_f32_e32 v212, v213, v212
	v_div_scale_f32 v213, vcc, 1.0, v210, 1.0
	v_mul_f32_e32 v220, v213, v212
	v_fma_f32 v221, -v211, v220, v213
	v_fmac_f32_e32 v220, v221, v212
	v_fma_f32 v211, -v211, v220, v213
	s_nop 0
	v_div_fmas_f32 v211, v211, v212, v220
	v_div_fixup_f32 v206, v211, v210, 1.0
	v_fmamk_f32 v185, v185, 0x3a000000, v222
	v_mul_f32_e32 v211, 0x4f800000, v185
	v_cmp_gt_f32_e32 vcc, 0xf800000, v185
	s_nop 1
	v_cndmask_b32_e32 v210, v185, v211, vcc
	v_sqrt_f32_e32 v211, v210
	s_nop 0
	v_add_u32_e32 v212, -1, v211
	v_fma_f32 v213, -v212, v211, v210
	v_cmp_ge_f32_e64 s[26:27], 0, v213
	v_add_u32_e32 v213, 1, v211
	s_nop 0
	v_cndmask_b32_e64 v212, v211, v212, s[26:27]
	v_fma_f32 v211, -v213, v211, v210
	v_cmp_lt_f32_e64 s[26:27], 0, v211
	s_nop 1
	v_cndmask_b32_e64 v211, v212, v213, s[26:27]
	v_mul_f32_e32 v212, 0x37800000, v211
	v_cndmask_b32_e32 v211, v211, v212, vcc
	v_cmp_class_f32_e32 vcc, v210, v223
	s_nop 1
	v_cndmask_b32_e32 v210, v211, v210, vcc
	v_div_scale_f32 v211, s[26:27], v210, v210, 1.0
	v_rcp_f32_e32 v212, v211
	s_nop 1
	v_fma_f32 v213, -v211, v212, 1.0
	v_fmac_f32_e32 v212, v213, v212
	v_div_scale_f32 v213, vcc, 1.0, v210, 1.0
	v_mul_f32_e32 v220, v213, v212
	v_fma_f32 v221, -v211, v220, v213
	v_fmac_f32_e32 v220, v221, v212
	v_fma_f32 v211, -v211, v220, v213
	s_nop 0
	v_div_fmas_f32 v211, v211, v212, v220
	v_div_fixup_f32 v208, v211, v210, 1.0
	v_readlane_b32 s100, v253, 50
	v_readlane_b32 s101, v253, 51
	s_add_u32 s100, s100, 0x4800000
	s_addc_u32 s101, s101, 0
	v_lshrrev_b32_e32 v157, 1, v153
	v_bfe_u32 v156, v153, 4, 1
	v_mad_u32_u24 v157, v156, 24, v157
	s_waitcnt vmcnt(0)
	v_add_f32_e32 v232, 1.0, v232
	v_add_f32_e32 v233, 1.0, v233
	v_add_f32_e32 v234, 1.0, v234
	v_add_f32_e32 v235, 1.0, v235
	v_add_f32_e32 v236, 1.0, v236
	v_add_f32_e32 v237, 1.0, v237
	v_add_f32_e32 v238, 1.0, v238
	v_add_f32_e32 v239, 1.0, v239
	v_add_f32_e32 v240, 1.0, v240
	v_add_f32_e32 v241, 1.0, v241
	v_add_f32_e32 v242, 1.0, v242
	v_add_f32_e32 v243, 1.0, v243
	v_add_f32_e32 v244, 1.0, v244
	v_add_f32_e32 v245, 1.0, v245
	v_add_f32_e32 v246, 1.0, v246
	v_add_f32_e32 v247, 1.0, v247
	v_add_u32_e32 v154, 0, v152
	v_lshl_add_u32 v154, v154, 12, v157
	v_pk_mul_f32 v[124:125], v[124:125], v[194:195] op_sel_hi:[1,0]
	v_pk_mul_f32 v[124:125], v[124:125], v[128:129]
	v_pk_fma_f32 v[124:125], v[124:125], v[232:233], v[162:163]
	v_pk_mul_f32 v[126:127], v[126:127], v[194:195] op_sel_hi:[1,0]
	v_pk_mul_f32 v[126:127], v[126:127], v[130:131]
	v_pk_fma_f32 v[126:127], v[126:127], v[234:235], v[164:165]
	v_pk_mul_f32 v[120:121], v[120:121], v[194:195] op_sel_hi:[1,0]
	v_pk_mul_f32 v[120:121], v[120:121], v[132:133]
	v_pk_fma_f32 v[120:121], v[120:121], v[236:237], v[166:167]
	v_pk_mul_f32 v[122:123], v[122:123], v[194:195] op_sel_hi:[1,0]
	v_pk_mul_f32 v[122:123], v[122:123], v[134:135]
	v_pk_fma_f32 v[122:123], v[122:123], v[238:239], v[168:169]
	v_cvt_pk_bf16_f32 v124, v124, v125
	v_cvt_pk_bf16_f32 v125, v126, v127
	v_cvt_pk_bf16_f32 v126, v120, v121
	v_cvt_pk_bf16_f32 v127, v122, v123
	s_nop 1
	v_permlane16_swap_b32_e32 v124, v126
	v_permlane16_swap_b32_e32 v125, v127
	v_pk_mul_f32 v[116:117], v[116:117], v[194:195] op_sel_hi:[1,0]
	v_pk_mul_f32 v[116:117], v[116:117], v[136:137]
	v_pk_fma_f32 v[116:117], v[116:117], v[240:241], v[170:171]
	v_pk_mul_f32 v[118:119], v[118:119], v[194:195] op_sel_hi:[1,0]
	v_pk_mul_f32 v[118:119], v[118:119], v[138:139]
	v_pk_fma_f32 v[118:119], v[118:119], v[242:243], v[172:173]
	v_pk_mul_f32 v[104:105], v[104:105], v[194:195] op_sel_hi:[1,0]
	v_pk_mul_f32 v[104:105], v[104:105], v[140:141]
	v_pk_fma_f32 v[104:105], v[104:105], v[244:245], v[248:249]
	v_pk_mul_f32 v[106:107], v[106:107], v[194:195] op_sel_hi:[1,0]
	v_pk_mul_f32 v[106:107], v[106:107], v[142:143]
	v_pk_fma_f32 v[106:107], v[106:107], v[246:247], v[250:251]
	v_cvt_pk_bf16_f32 v116, v116, v117
	v_cvt_pk_bf16_f32 v117, v118, v119
	v_cvt_pk_bf16_f32 v118, v104, v105
	v_cvt_pk_bf16_f32 v119, v106, v107
	s_nop 1
	v_permlane16_swap_b32_e32 v116, v118
	v_permlane16_swap_b32_e32 v117, v119
	global_store_dwordx4 v154, v[124:127], s[100:101] offset:0 sc1
	global_store_dwordx4 v154, v[116:119], s[100:101] offset:256 sc1
	v_add_u32_e32 v154, 16, v152
	v_lshl_add_u32 v154, v154, 12, v157
	v_pk_mul_f32 v[112:113], v[112:113], v[196:197] op_sel_hi:[1,0]
	v_pk_mul_f32 v[112:113], v[112:113], v[128:129]
	v_pk_fma_f32 v[112:113], v[112:113], v[232:233], v[162:163]
	v_pk_mul_f32 v[114:115], v[114:115], v[196:197] op_sel_hi:[1,0]
	v_pk_mul_f32 v[114:115], v[114:115], v[130:131]
	v_pk_fma_f32 v[114:115], v[114:115], v[234:235], v[164:165]
	v_pk_mul_f32 v[108:109], v[108:109], v[196:197] op_sel_hi:[1,0]
	v_pk_mul_f32 v[108:109], v[108:109], v[132:133]
	v_pk_fma_f32 v[108:109], v[108:109], v[236:237], v[166:167]
	v_pk_mul_f32 v[110:111], v[110:111], v[196:197] op_sel_hi:[1,0]
	v_pk_mul_f32 v[110:111], v[110:111], v[134:135]
	v_pk_fma_f32 v[110:111], v[110:111], v[238:239], v[168:169]
	v_cvt_pk_bf16_f32 v112, v112, v113
	v_cvt_pk_bf16_f32 v113, v114, v115
	v_cvt_pk_bf16_f32 v114, v108, v109
	v_cvt_pk_bf16_f32 v115, v110, v111
	s_nop 1
	v_permlane16_swap_b32_e32 v112, v114
	v_permlane16_swap_b32_e32 v113, v115
	v_pk_mul_f32 v[96:97], v[96:97], v[196:197] op_sel_hi:[1,0]
	v_pk_mul_f32 v[96:97], v[96:97], v[136:137]
	v_pk_fma_f32 v[96:97], v[96:97], v[240:241], v[170:171]
	v_pk_mul_f32 v[98:99], v[98:99], v[196:197] op_sel_hi:[1,0]
	v_pk_mul_f32 v[98:99], v[98:99], v[138:139]
	v_pk_fma_f32 v[98:99], v[98:99], v[242:243], v[172:173]
	v_pk_mul_f32 v[88:89], v[88:89], v[196:197] op_sel_hi:[1,0]
	v_pk_mul_f32 v[88:89], v[88:89], v[140:141]
	v_pk_fma_f32 v[88:89], v[88:89], v[244:245], v[248:249]
	v_pk_mul_f32 v[90:91], v[90:91], v[196:197] op_sel_hi:[1,0]
	v_pk_mul_f32 v[90:91], v[90:91], v[142:143]
	v_pk_fma_f32 v[90:91], v[90:91], v[246:247], v[250:251]
	v_cvt_pk_bf16_f32 v96, v96, v97
	v_cvt_pk_bf16_f32 v97, v98, v99
	v_cvt_pk_bf16_f32 v98, v88, v89
	v_cvt_pk_bf16_f32 v99, v90, v91
	s_nop 1
	v_permlane16_swap_b32_e32 v96, v98
	v_permlane16_swap_b32_e32 v97, v99
	global_store_dwordx4 v154, v[112:115], s[100:101] offset:0 sc1
	global_store_dwordx4 v154, v[96:99], s[100:101] offset:256 sc1
	v_add_u32_e32 v154, 32, v152
	v_lshl_add_u32 v154, v154, 12, v157
	v_pk_mul_f32 v[100:101], v[100:101], v[198:199] op_sel_hi:[1,0]
	v_pk_mul_f32 v[100:101], v[100:101], v[128:129]
	v_pk_fma_f32 v[100:101], v[100:101], v[232:233], v[162:163]
	v_pk_mul_f32 v[102:103], v[102:103], v[198:199] op_sel_hi:[1,0]
	v_pk_mul_f32 v[102:103], v[102:103], v[130:131]
	v_pk_fma_f32 v[102:103], v[102:103], v[234:235], v[164:165]
	v_pk_mul_f32 v[92:93], v[92:93], v[198:199] op_sel_hi:[1,0]
	v_pk_mul_f32 v[92:93], v[92:93], v[132:133]
	v_pk_fma_f32 v[92:93], v[92:93], v[236:237], v[166:167]
	v_pk_mul_f32 v[94:95], v[94:95], v[198:199] op_sel_hi:[1,0]
	v_pk_mul_f32 v[94:95], v[94:95], v[134:135]
	v_pk_fma_f32 v[94:95], v[94:95], v[238:239], v[168:169]
	v_cvt_pk_bf16_f32 v100, v100, v101
	v_cvt_pk_bf16_f32 v101, v102, v103
	v_cvt_pk_bf16_f32 v102, v92, v93
	v_cvt_pk_bf16_f32 v103, v94, v95
	s_nop 1
	v_permlane16_swap_b32_e32 v100, v102
	v_permlane16_swap_b32_e32 v101, v103
	v_pk_mul_f32 v[80:81], v[80:81], v[198:199] op_sel_hi:[1,0]
	v_pk_mul_f32 v[80:81], v[80:81], v[136:137]
	v_pk_fma_f32 v[80:81], v[80:81], v[240:241], v[170:171]
	v_pk_mul_f32 v[82:83], v[82:83], v[198:199] op_sel_hi:[1,0]
	v_pk_mul_f32 v[82:83], v[82:83], v[138:139]
	v_pk_fma_f32 v[82:83], v[82:83], v[242:243], v[172:173]
	v_pk_mul_f32 v[72:73], v[72:73], v[198:199] op_sel_hi:[1,0]
	v_pk_mul_f32 v[72:73], v[72:73], v[140:141]
	v_pk_fma_f32 v[72:73], v[72:73], v[244:245], v[248:249]
	v_pk_mul_f32 v[74:75], v[74:75], v[198:199] op_sel_hi:[1,0]
	v_pk_mul_f32 v[74:75], v[74:75], v[142:143]
	v_pk_fma_f32 v[74:75], v[74:75], v[246:247], v[250:251]
	v_cvt_pk_bf16_f32 v80, v80, v81
	v_cvt_pk_bf16_f32 v81, v82, v83
	v_cvt_pk_bf16_f32 v82, v72, v73
	v_cvt_pk_bf16_f32 v83, v74, v75
	s_nop 1
	v_permlane16_swap_b32_e32 v80, v82
	v_permlane16_swap_b32_e32 v81, v83
	global_store_dwordx4 v154, v[100:103], s[100:101] offset:0 sc1
	global_store_dwordx4 v154, v[80:83], s[100:101] offset:256 sc1
	v_add_u32_e32 v154, 48, v152
	v_lshl_add_u32 v154, v154, 12, v157
	v_pk_mul_f32 v[84:85], v[84:85], v[200:201] op_sel_hi:[1,0]
	v_pk_mul_f32 v[84:85], v[84:85], v[128:129]
	v_pk_fma_f32 v[84:85], v[84:85], v[232:233], v[162:163]
	v_pk_mul_f32 v[86:87], v[86:87], v[200:201] op_sel_hi:[1,0]
	v_pk_mul_f32 v[86:87], v[86:87], v[130:131]
	v_pk_fma_f32 v[86:87], v[86:87], v[234:235], v[164:165]
	v_pk_mul_f32 v[76:77], v[76:77], v[200:201] op_sel_hi:[1,0]
	v_pk_mul_f32 v[76:77], v[76:77], v[132:133]
	v_pk_fma_f32 v[76:77], v[76:77], v[236:237], v[166:167]
	v_pk_mul_f32 v[78:79], v[78:79], v[200:201] op_sel_hi:[1,0]
	v_pk_mul_f32 v[78:79], v[78:79], v[134:135]
	v_pk_fma_f32 v[78:79], v[78:79], v[238:239], v[168:169]
	v_cvt_pk_bf16_f32 v84, v84, v85
	v_cvt_pk_bf16_f32 v85, v86, v87
	v_cvt_pk_bf16_f32 v86, v76, v77
	v_cvt_pk_bf16_f32 v87, v78, v79
	s_nop 1
	v_permlane16_swap_b32_e32 v84, v86
	v_permlane16_swap_b32_e32 v85, v87
	v_pk_mul_f32 v[68:69], v[68:69], v[200:201] op_sel_hi:[1,0]
	v_pk_mul_f32 v[68:69], v[68:69], v[136:137]
	v_pk_fma_f32 v[68:69], v[68:69], v[240:241], v[170:171]
	v_pk_mul_f32 v[70:71], v[70:71], v[200:201] op_sel_hi:[1,0]
	v_pk_mul_f32 v[70:71], v[70:71], v[138:139]
	v_pk_fma_f32 v[70:71], v[70:71], v[242:243], v[172:173]
	v_pk_mul_f32 v[64:65], v[64:65], v[200:201] op_sel_hi:[1,0]
	v_pk_mul_f32 v[64:65], v[64:65], v[140:141]
	v_pk_fma_f32 v[64:65], v[64:65], v[244:245], v[248:249]
	v_pk_mul_f32 v[66:67], v[66:67], v[200:201] op_sel_hi:[1,0]
	v_pk_mul_f32 v[66:67], v[66:67], v[142:143]
	v_pk_fma_f32 v[66:67], v[66:67], v[246:247], v[250:251]
	v_cvt_pk_bf16_f32 v68, v68, v69
	v_cvt_pk_bf16_f32 v69, v70, v71
	v_cvt_pk_bf16_f32 v70, v64, v65
	v_cvt_pk_bf16_f32 v71, v66, v67
	s_nop 1
	v_permlane16_swap_b32_e32 v68, v70
	v_permlane16_swap_b32_e32 v69, v71
	global_store_dwordx4 v154, v[84:87], s[100:101] offset:0 sc1
	global_store_dwordx4 v154, v[68:71], s[100:101] offset:256 sc1
	v_add_u32_e32 v154, 128, v152
	v_lshl_add_u32 v154, v154, 12, v157
	v_pk_mul_f32 v[60:61], v[60:61], v[202:203] op_sel_hi:[1,0]
	v_pk_mul_f32 v[60:61], v[60:61], v[128:129]
	v_pk_fma_f32 v[60:61], v[60:61], v[232:233], v[162:163]
	v_pk_mul_f32 v[62:63], v[62:63], v[202:203] op_sel_hi:[1,0]
	v_pk_mul_f32 v[62:63], v[62:63], v[130:131]
	v_pk_fma_f32 v[62:63], v[62:63], v[234:235], v[164:165]
	v_pk_mul_f32 v[56:57], v[56:57], v[202:203] op_sel_hi:[1,0]
	v_pk_mul_f32 v[56:57], v[56:57], v[132:133]
	v_pk_fma_f32 v[56:57], v[56:57], v[236:237], v[166:167]
	v_pk_mul_f32 v[58:59], v[58:59], v[202:203] op_sel_hi:[1,0]
	v_pk_mul_f32 v[58:59], v[58:59], v[134:135]
	v_pk_fma_f32 v[58:59], v[58:59], v[238:239], v[168:169]
	v_cvt_pk_bf16_f32 v60, v60, v61
	v_cvt_pk_bf16_f32 v61, v62, v63
	v_cvt_pk_bf16_f32 v62, v56, v57
	v_cvt_pk_bf16_f32 v63, v58, v59
	s_nop 1
	v_permlane16_swap_b32_e32 v60, v62
	v_permlane16_swap_b32_e32 v61, v63
	v_pk_mul_f32 v[48:49], v[48:49], v[202:203] op_sel_hi:[1,0]
	v_pk_mul_f32 v[48:49], v[48:49], v[136:137]
	v_pk_fma_f32 v[48:49], v[48:49], v[240:241], v[170:171]
	v_pk_mul_f32 v[50:51], v[50:51], v[202:203] op_sel_hi:[1,0]
	v_pk_mul_f32 v[50:51], v[50:51], v[138:139]
	v_pk_fma_f32 v[50:51], v[50:51], v[242:243], v[172:173]
	v_pk_mul_f32 v[40:41], v[40:41], v[202:203] op_sel_hi:[1,0]
	v_pk_mul_f32 v[40:41], v[40:41], v[140:141]
	v_pk_fma_f32 v[40:41], v[40:41], v[244:245], v[248:249]
	v_pk_mul_f32 v[42:43], v[42:43], v[202:203] op_sel_hi:[1,0]
	v_pk_mul_f32 v[42:43], v[42:43], v[142:143]
	v_pk_fma_f32 v[42:43], v[42:43], v[246:247], v[250:251]
	v_cvt_pk_bf16_f32 v48, v48, v49
	v_cvt_pk_bf16_f32 v49, v50, v51
	v_cvt_pk_bf16_f32 v50, v40, v41
	v_cvt_pk_bf16_f32 v51, v42, v43
	s_nop 1
	v_permlane16_swap_b32_e32 v48, v50
	v_permlane16_swap_b32_e32 v49, v51
	global_store_dwordx4 v154, v[60:63], s[100:101] offset:0 sc1
	global_store_dwordx4 v154, v[48:51], s[100:101] offset:256 sc1
	v_add_u32_e32 v154, 144, v152
	v_lshl_add_u32 v154, v154, 12, v157
	v_pk_mul_f32 v[52:53], v[52:53], v[204:205] op_sel_hi:[1,0]
	v_pk_mul_f32 v[52:53], v[52:53], v[128:129]
	v_pk_fma_f32 v[52:53], v[52:53], v[232:233], v[162:163]
	v_pk_mul_f32 v[54:55], v[54:55], v[204:205] op_sel_hi:[1,0]
	v_pk_mul_f32 v[54:55], v[54:55], v[130:131]
	v_pk_fma_f32 v[54:55], v[54:55], v[234:235], v[164:165]
	v_pk_mul_f32 v[44:45], v[44:45], v[204:205] op_sel_hi:[1,0]
	v_pk_mul_f32 v[44:45], v[44:45], v[132:133]
	v_pk_fma_f32 v[44:45], v[44:45], v[236:237], v[166:167]
	v_pk_mul_f32 v[46:47], v[46:47], v[204:205] op_sel_hi:[1,0]
	v_pk_mul_f32 v[46:47], v[46:47], v[134:135]
	v_pk_fma_f32 v[46:47], v[46:47], v[238:239], v[168:169]
	v_cvt_pk_bf16_f32 v52, v52, v53
	v_cvt_pk_bf16_f32 v53, v54, v55
	v_cvt_pk_bf16_f32 v54, v44, v45
	v_cvt_pk_bf16_f32 v55, v46, v47
	s_nop 1
	v_permlane16_swap_b32_e32 v52, v54
	v_permlane16_swap_b32_e32 v53, v55
	v_pk_mul_f32 v[32:33], v[32:33], v[204:205] op_sel_hi:[1,0]
	v_pk_mul_f32 v[32:33], v[32:33], v[136:137]
	v_pk_fma_f32 v[32:33], v[32:33], v[240:241], v[170:171]
	v_pk_mul_f32 v[34:35], v[34:35], v[204:205] op_sel_hi:[1,0]
	v_pk_mul_f32 v[34:35], v[34:35], v[138:139]
	v_pk_fma_f32 v[34:35], v[34:35], v[242:243], v[172:173]
	v_pk_mul_f32 v[24:25], v[24:25], v[204:205] op_sel_hi:[1,0]
	v_pk_mul_f32 v[24:25], v[24:25], v[140:141]
	v_pk_fma_f32 v[24:25], v[24:25], v[244:245], v[248:249]
	v_pk_mul_f32 v[26:27], v[26:27], v[204:205] op_sel_hi:[1,0]
	v_pk_mul_f32 v[26:27], v[26:27], v[142:143]
	v_pk_fma_f32 v[26:27], v[26:27], v[246:247], v[250:251]
	v_cvt_pk_bf16_f32 v32, v32, v33
	v_cvt_pk_bf16_f32 v33, v34, v35
	v_cvt_pk_bf16_f32 v34, v24, v25
	v_cvt_pk_bf16_f32 v35, v26, v27
	s_nop 1
	v_permlane16_swap_b32_e32 v32, v34
	v_permlane16_swap_b32_e32 v33, v35
	global_store_dwordx4 v154, v[52:55], s[100:101] offset:0 sc1
	global_store_dwordx4 v154, v[32:35], s[100:101] offset:256 sc1
	v_add_u32_e32 v154, 160, v152
	v_lshl_add_u32 v154, v154, 12, v157
	v_pk_mul_f32 v[36:37], v[36:37], v[206:207] op_sel_hi:[1,0]
	v_pk_mul_f32 v[36:37], v[36:37], v[128:129]
	v_pk_fma_f32 v[36:37], v[36:37], v[232:233], v[162:163]
	v_pk_mul_f32 v[38:39], v[38:39], v[206:207] op_sel_hi:[1,0]
	v_pk_mul_f32 v[38:39], v[38:39], v[130:131]
	v_pk_fma_f32 v[38:39], v[38:39], v[234:235], v[164:165]
	v_pk_mul_f32 v[28:29], v[28:29], v[206:207] op_sel_hi:[1,0]
	v_pk_mul_f32 v[28:29], v[28:29], v[132:133]
	v_pk_fma_f32 v[28:29], v[28:29], v[236:237], v[166:167]
	v_pk_mul_f32 v[30:31], v[30:31], v[206:207] op_sel_hi:[1,0]
	v_pk_mul_f32 v[30:31], v[30:31], v[134:135]
	v_pk_fma_f32 v[30:31], v[30:31], v[238:239], v[168:169]
	v_cvt_pk_bf16_f32 v36, v36, v37
	v_cvt_pk_bf16_f32 v37, v38, v39
	v_cvt_pk_bf16_f32 v38, v28, v29
	v_cvt_pk_bf16_f32 v39, v30, v31
	s_nop 1
	v_permlane16_swap_b32_e32 v36, v38
	v_permlane16_swap_b32_e32 v37, v39
	v_pk_mul_f32 v[20:21], v[20:21], v[206:207] op_sel_hi:[1,0]
	v_pk_mul_f32 v[20:21], v[20:21], v[136:137]
	v_pk_fma_f32 v[20:21], v[20:21], v[240:241], v[170:171]
	v_pk_mul_f32 v[22:23], v[22:23], v[206:207] op_sel_hi:[1,0]
	v_pk_mul_f32 v[22:23], v[22:23], v[138:139]
	v_pk_fma_f32 v[22:23], v[22:23], v[242:243], v[172:173]
	v_pk_mul_f32 v[12:13], v[12:13], v[206:207] op_sel_hi:[1,0]
	v_pk_mul_f32 v[12:13], v[12:13], v[140:141]
	v_pk_fma_f32 v[12:13], v[12:13], v[244:245], v[248:249]
	v_pk_mul_f32 v[14:15], v[14:15], v[206:207] op_sel_hi:[1,0]
	v_pk_mul_f32 v[14:15], v[14:15], v[142:143]
	v_pk_fma_f32 v[14:15], v[14:15], v[246:247], v[250:251]
	v_cvt_pk_bf16_f32 v20, v20, v21
	v_cvt_pk_bf16_f32 v21, v22, v23
	v_cvt_pk_bf16_f32 v22, v12, v13
	v_cvt_pk_bf16_f32 v23, v14, v15
	s_nop 1
	v_permlane16_swap_b32_e32 v20, v22
	v_permlane16_swap_b32_e32 v21, v23
	global_store_dwordx4 v154, v[36:39], s[100:101] offset:0 sc1
	global_store_dwordx4 v154, v[20:23], s[100:101] offset:256 sc1
	v_add_u32_e32 v154, 176, v152
	v_lshl_add_u32 v154, v154, 12, v157
	v_pk_mul_f32 v[16:17], v[16:17], v[208:209] op_sel_hi:[1,0]
	v_pk_mul_f32 v[16:17], v[16:17], v[128:129]
	v_pk_fma_f32 v[16:17], v[16:17], v[232:233], v[162:163]
	v_pk_mul_f32 v[18:19], v[18:19], v[208:209] op_sel_hi:[1,0]
	v_pk_mul_f32 v[18:19], v[18:19], v[130:131]
	v_pk_fma_f32 v[18:19], v[18:19], v[234:235], v[164:165]
	v_pk_mul_f32 v[8:9], v[8:9], v[208:209] op_sel_hi:[1,0]
	v_pk_mul_f32 v[8:9], v[8:9], v[132:133]
	v_pk_fma_f32 v[8:9], v[8:9], v[236:237], v[166:167]
	v_pk_mul_f32 v[10:11], v[10:11], v[208:209] op_sel_hi:[1,0]
	v_pk_mul_f32 v[10:11], v[10:11], v[134:135]
	v_pk_fma_f32 v[10:11], v[10:11], v[238:239], v[168:169]
	v_cvt_pk_bf16_f32 v16, v16, v17
	v_cvt_pk_bf16_f32 v17, v18, v19
	v_cvt_pk_bf16_f32 v18, v8, v9
	v_cvt_pk_bf16_f32 v19, v10, v11
	s_nop 1
	v_permlane16_swap_b32_e32 v16, v18
	v_permlane16_swap_b32_e32 v17, v19
	v_pk_mul_f32 v[4:5], v[4:5], v[208:209] op_sel_hi:[1,0]
	v_pk_mul_f32 v[4:5], v[4:5], v[136:137]
	v_pk_fma_f32 v[4:5], v[4:5], v[240:241], v[170:171]
	v_pk_mul_f32 v[6:7], v[6:7], v[208:209] op_sel_hi:[1,0]
	v_pk_mul_f32 v[6:7], v[6:7], v[138:139]
	v_pk_fma_f32 v[6:7], v[6:7], v[242:243], v[172:173]
	v_pk_mul_f32 v[0:1], v[0:1], v[208:209] op_sel_hi:[1,0]
	v_pk_mul_f32 v[0:1], v[0:1], v[140:141]
	v_pk_fma_f32 v[0:1], v[0:1], v[244:245], v[248:249]
	v_pk_mul_f32 v[2:3], v[2:3], v[208:209] op_sel_hi:[1,0]
	v_pk_mul_f32 v[2:3], v[2:3], v[142:143]
	v_pk_fma_f32 v[2:3], v[2:3], v[246:247], v[250:251]
	v_cvt_pk_bf16_f32 v4, v4, v5
	v_cvt_pk_bf16_f32 v5, v6, v7
	v_cvt_pk_bf16_f32 v6, v0, v1
	v_cvt_pk_bf16_f32 v7, v2, v3
	s_nop 1
	v_permlane16_swap_b32_e32 v4, v6
	v_permlane16_swap_b32_e32 v5, v7
	global_store_dwordx4 v154, v[16:19], s[100:101] offset:0 sc1
	global_store_dwordx4 v154, v[4:7], s[100:101] offset:256 sc1
	s_branch .LBB0_1269
.LBB0_1266:
	s_cmp_lg_u64 s[78:79], 0
	s_cbranch_scc1 .Lf7_start
	s_mov_b64 s[20:21], -1

.Lgb7_done:
.LBB0_1318:
	s_or_b64 exec, exec, s[2:3]
	v_mov_b32_e32 v0, v214
	v_readlane_b32 s3, v253, 0
	s_waitcnt lgkmcnt(0)
	s_barrier
	s_lshl_b32 s3, s3, 3
	v_readfirstlane_b32 s2, v0
	s_ashr_i32 s2, s2, 6
	s_add_i32 s2, s3, s2
	s_cmp_lg_u64 s[78:79], 0
	s_cbranch_scc1 .LBB0_1325
	s_cmpk_gt_i32 s2, 0x23ff
	s_cbranch_scc1 .LBB0_1325
	v_readlane_b32 s4, v254, 57
	v_readlane_b32 s5, v254, 58
	s_and_b64 s[4:5], s[4:5], exec
	v_readlane_b32 s4, v253, 62
	v_lshlrev_b32_e32 v1, 2, v0
	v_readlane_b32 s5, v253, 63
	v_and_b32_e32 v2, 0xfc, v1
	s_cselect_b32 s5, s5, 0
	s_cselect_b32 s4, s4, 0
	v_lshlrev_b32_e32 v176, 2, v2
	v_lshl_add_u64 v[32:33], s[4:5], 0, v[176:177]
	v_readlane_b32 s4, v254, 53
	v_readlane_b32 s5, v254, 54
	v_readlane_b32 s8, v253, 7
	s_lshl_b64 s[6:7], s[50:51], 2
	v_lshl_add_u64 v[34:35], s[4:5], 0, v[176:177]
	s_mov_b64 s[4:5], 0x34000
	v_lshl_add_u64 v[36:37], v[34:35], 0, s[4:5]
	s_mov_b64 s[4:5], 0x35000
	v_readlane_b32 s22, v253, 21
	v_lshl_add_u64 v[40:41], v[34:35], 0, s[4:5]
	s_mov_b64 s[4:5], 0x35400
	v_readlane_b32 s23, v253, 22
	s_add_u32 s6, s22, s6
	v_lshl_add_u64 v[42:43], v[34:35], 0, s[4:5]
	s_mov_b64 s[4:5], 0x35800
	s_addc_u32 s7, s23, s7
	v_lshl_add_u64 v[44:45], v[34:35], 0, s[4:5]
	s_mov_b64 s[4:5], 0x35c00
	v_lshl_add_u64 v[38:39], s[6:7], 0, v[176:177]
	v_lshl_add_u64 v[46:47], v[34:35], 0, s[4:5]
	s_mov_b64 s[4:5], 0x1000
	v_lshl_add_u64 v[48:49], v[38:39], 0, s[4:5]
	s_mov_b64 s[4:5], 0x1400
	v_lshl_add_u64 v[50:51], v[38:39], 0, s[4:5]
	s_mov_b64 s[4:5], 0x1800
	v_lshl_add_u64 v[52:53], v[38:39], 0, s[4:5]
	s_mov_b64 s[4:5], 0x1c00
	s_ashr_i32 s3, s2, 31
	v_lshl_add_u64 v[54:55], v[38:39], 0, s[4:5]
	s_lshl_b64 s[4:5], s[2:3], 13
	v_and_b32_e32 v0, 63, v0
	v_lshl_or_b32 v56, v0, 4, s4
	v_mov_b32_e32 v57, s5
	s_lshl_b64 s[4:5], s[2:3], 12
	v_lshl_or_b32 v58, v0, 3, s4
	v_mov_b32_e32 v59, s5
	v_lshlrev_b32_e32 v176, 2, v2
	v_readlane_b32 s9, v253, 8
	v_readlane_b32 s10, v253, 9
	v_readlane_b32 s11, v253, 10
	v_readlane_b32 s12, v253, 11
	v_readlane_b32 s13, v253, 12
	v_readlane_b32 s14, v253, 13
	v_readlane_b32 s15, v253, 14
	v_readlane_b32 s16, v253, 15
	v_readlane_b32 s17, v253, 16
	v_readlane_b32 s18, v253, 17
	v_readlane_b32 s19, v253, 18
	v_readlane_b32 s20, v253, 19
	v_readlane_b32 s21, v253, 20
	s_branch .LBB0_1322
.LBB0_1322:
	s_cmp_lg_u32 s2, 0
	s_cbranch_scc1 .Lfz_zskip
	v_lshrrev_b32_e32 v211, 2, v176
	v_mov_b32_e32 v212, 0
	s_add_u32 s10, s54, 0xe0000
	s_addc_u32 s11, s55, 0
	global_store_dword v211, v212, s[10:11] sc1
	global_store_dword v211, v212, s[10:11] offset:256 sc1

.Lnrm_p7_exit:
.LBB0_1325:
	s_waitcnt vmcnt(0)
	s_barrier
	s_mov_b64 s[2:3], exec
	v_readlane_b32 s4, v253, 42
	v_readlane_b32 s5, v253, 43
	s_and_b64 s[4:5], s[2:3], s[4:5]
	s_cmp_lg_u64 s[78:79], 0
	s_cselect_b64 s[4:5], 0, s[4:5]
	s_movk_i32 s92, 0x2c00
	s_mov_b64 exec, s[4:5]
	s_cbranch_execz .LBB0_1369
	v_readlane_b32 s6, v253, 39
	v_readlane_b32 s7, v253, 40
	v_readlane_b32 s8, v253, 41
	v_readlane_b32 s9, v255, 20
	v_mov_b32_e32 v0, 0x23fc0
	ds_read2_b32 v[4:5], v0 offset1:1
	s_add_i32 s9, s9, 1
	v_writelane_b32 v255, s9, 20
	s_lshl_b32 s10, s8, 8
	s_add_i32 s10, s10, 0x1400
	v_mov_b32_e32 v0, s10
	v_mov_b32_e32 v1, 1
	global_atomic_add v2, v0, v1, s[6:7] sc0
	buffer_inv sc1
	s_waitcnt vmcnt(0) lgkmcnt(0)
	v_readfirstlane_b32 s11, v2
	v_readfirstlane_b32 s15, v4
	v_readfirstlane_b32 s14, v5
	s_add_i32 s11, s11, 1
	s_mul_i32 s15, s15, s9
	s_cmp_lg_u32 s11, s15
	s_cbranch_scc1 .Lgb8_wait
	buffer_wbl2 sc1
	s_waitcnt vmcnt(0)
	s_mov_b64 exec, 0xffff
	v_mbcnt_lo_u32_b32 v3, -1, 0
	v_lshlrev_b32_e32 v3, 8, v3
	v_add_u32_e32 v3, 0x2480, v3
	v_mov_b32_e32 v1, 1
	global_atomic_add v3, v1, s[6:7]
	s_mov_b64 exec, 1

.Lfz_poll:
	s_sleep 1
	global_load_dword v155, v154, s[100:101] sc1
	s_waitcnt vmcnt(0)
	s_nop 0
	v_readfirstlane_b32 s18, v155
	s_add_i32 s19, s19, 1
	s_cmp_ge_u32 s18, 8
	s_cbranch_scc1 .Lfz_synced
	s_cmp_lt_u32 s19, 0x400000
	s_cbranch_scc1 .Lfz_poll
